# NA item-order permutation now guarded by gridDim==256 (identity otherwise); phase-0 GEMV rolling window; otherwise as the previous best
# speedup vs baseline: 1.0025x; 1.0025x over previous
.LBB0_1069:
	s_and_b32 s100, s45, 0x700
	s_and_b32 s101, s45, 7
	s_lshl_b32 s101, s101, 5
	s_or_b32 s100, s100, s101
	s_bfe_u32 s101, s45, 0x20006
	s_lshl_b32 s101, s101, 3
	s_or_b32 s100, s100, s101
	s_bfe_u32 s101, s45, 0x30003
	s_or_b32 s100, s100, s101
	s_cmpk_eq_i32 s14, 0x100
	s_cselect_b32 s100, s100, s45
	s_and_b32 s48, s100, 7
	s_lshl_b32 s49, s48, 2
	s_add_i32 s47, s49, s11
	v_or_b32_e32 v2, s47, v108
	v_lshl_add_u32 v0, v2, 6, v109
	s_ashr_i32 s30, s100, 7
	v_ashrrev_i32_e32 v1, 31, v0
	v_mad_i64_i32 v[102:103], s[12:13], s30, v130, v[0:1]
	v_readlane_b32 s72, v239, 32
	s_bfe_u32 s40, s100, 0x40003
	v_lshlrev_b64 v[0:1], 11, v[102:103]
	v_readlane_b32 s74, v239, 34
	v_readlane_b32 s75, v239, 35
	s_lshl_b32 s22, s40, 7
	s_lshl_b32 s46, s40, 6
	v_lshl_add_u64 v[0:1], s[74:75], 0, v[0:1]
	v_lshl_add_u64 v[0:1], v[0:1], 0, s[22:23]
	v_lshl_add_u64 v[0:1], v[0:1], 0, v[98:99]
	global_load_dwordx4 v[64:67], v[0:1], off
	global_load_dwordx4 v[68:71], v[0:1], off offset:32
	global_load_dwordx4 v[72:75], v[0:1], off offset:64
	global_load_dwordx4 v[76:79], v[0:1], off offset:96
	v_mad_i64_i32 v[0:1], s[12:13], s30, v130, v[92:93]
	s_mul_hi_i32 s13, s30, 0xfffffb00
	s_mulk_i32 s30, 0xfb00
	v_readlane_b32 s76, v239, 36
	v_readlane_b32 s77, v239, 37
	v_lshlrev_b64 v[4:5], 11, v[0:1]
	s_add_u32 s12, s46, s30
	v_lshl_add_u64 v[4:5], s[76:77], 0, v[4:5]
	s_addc_u32 s13, 0, s13
	v_lshl_add_u64 v[4:5], v[4:5], 0, s[22:23]
	v_lshl_add_u64 v[0:1], s[12:13], 0, v[0:1]
	v_lshl_add_u64 v[104:105], v[4:5], 0, v[100:101]
	v_mad_u64_u32 v[106:107], s[12:13], v0, s33, v[96:97]
	v_mad_i32_i24 v107, v1, s33, v107
	global_load_dwordx4 v[80:83], v[104:105], off
	global_load_dwordx4 v[84:87], v[106:107], off
	v_med3_u32 v0, s49, 1, 25
	v_readlane_b32 s73, v239, 33
	v_readfirstlane_b32 s50, v0
	v_readlane_b32 s78, v239, 38
	v_readlane_b32 s79, v239, 39
	s_waitcnt vmcnt(63) expcnt(7) lgkmcnt(15)
	s_barrier
	s_and_saveexec_b64 s[12:13], s[0:1]
	s_cbranch_execz .LBB0_1082
	s_mov_b64 s[38:39], -1
	v_mov_b32_e32 v0, v90
	s_and_saveexec_b64 s[30:31], s[2:3]
	s_cbranch_execz .LBB0_1079
	s_mulk_i32 s40, 0x744
	s_add_u32 s38, s56, s40
	s_addc_u32 s39, s57, 0
	v_mov_b32_e32 v5, 0
	v_mov_b64_e32 v[0:1], v[90:91]
	s_and_saveexec_b64 s[40:41], s[4:5]
	s_cbranch_execz .LBB0_1075
	s_mov_b32 s22, 0
	s_mov_b64 s[42:43], 0
	v_mov_b32_e32 v3, v127
	v_mov_b32_e32 v4, v126
	v_mov_b64_e32 v[0:1], v[90:91]
